# plus: helpers run a ready x1=x+m@w_out unit while the next merge unit still waits for the scan
# speedup vs baseline: 1.0111x; 1.0014x over previous
.LBB0_537:
	s_or_b64 exec, exec, s[0:1]
	s_and_b64 s[0:1], s[36:37], exec
	s_cselect_b32 s28, 16, 0x1000
	s_add_u32 s64, s76, 0x13d00000
	s_addc_u32 s65, s77, 0
	s_bfe_u32 s68, s96, 0x20006
	s_mul_i32 s0, s68, 0x3700
	s_add_i32 s71, s0, 0
	s_and_b32 s0, s96, 0xffffff00
	s_lshr_b32 s74, s96, 8
	s_add_i32 s84, s0, 0
	s_lshl_b32 s11, s74, 5
	s_add_i32 s80, s84, 0x12600
	s_cmpk_lt_u32 s96, 0x540
	v_readlane_b32 s20, v255, 31
	s_cselect_b64 s[40:41], -1, 0
	s_add_i32 s12, s20, -4
	s_lshl_b32 s13, s12, 2
	s_lshl_b32 s22, s12, 10
	s_cmpk_lt_u32 s96, 0x440
	s_cselect_b64 s[42:43], -1, 0
	s_lshl_b32 s66, s20, 10
	s_cmpk_lt_u32 s96, 0x340
	s_cselect_b64 s[46:47], -1, 0
	s_add_i32 s14, s20, 4
	s_lshl_b32 s15, s14, 2
	s_lshl_b32 s23, s14, 10
	s_cmpk_lt_u32 s96, 0x240
	s_cselect_b64 s[48:49], -1, 0
	s_add_i32 s16, s20, 8
	s_lshl_b32 s17, s16, 2
	s_lshl_b32 s24, s16, 10
	s_cmp_eq_u32 s20, 4
	s_cselect_b64 s[50:51], -1, 0
	s_cmp_eq_u32 s20, 2
	s_mov_b32 s0, 0xfc00000
	s_cselect_b32 s38, s0, 0x13d00000
	s_add_u32 s8, s76, s6
	s_addc_u32 s9, s77, 0
	s_mul_i32 s0, s20, 0x2400
	s_add_i32 s1, 0, 0x1a900
	s_add_i32 s81, s1, s0
	s_lshl_b32 s0, s74, 7
	s_add_i32 s83, s0, 0
	s_add_i32 s82, s81, 0x2000
	s_add_i32 s83, s83, 0x14800
	s_add_i32 s84, s84, 0x12400
	s_lshl_b32 s29, s20, 5
	s_add_u32 s6, s64, s6
	s_addc_u32 s7, s65, 0
	s_lshl_b32 s85, s33, 10
	s_add_u32 s18, s76, 0x10000
	v_writelane_b32 v255, s96, 33
	s_addc_u32 s19, s77, 0
	v_lshl_or_b32 v11, s68, 4, v9
	v_writelane_b32 v255, s18, 34
	v_add_u32_e32 v25, 1, v11
	v_lshlrev_b32_e32 v27, 3, v38
	v_writelane_b32 v255, s19, 35
	v_lshlrev_b32_e32 v10, 7, v25
	v_and_b32_e32 v22, 8, v27
	s_add_i32 s0, 0, 0x1cd00
	s_add_i32 s18, 0, 0x1f100
	v_add3_u32 v91, s1, v10, v22
	v_add3_u32 v92, s0, v10, v22
	v_add3_u32 v93, s18, v10, v22
	v_lshlrev_b32_e32 v10, 8, v25
	s_add_i32 s19, 0, 0x23900
	v_add3_u32 v28, s19, v10, v22
	v_lshlrev_b32_e32 v10, 7, v11
	v_add3_u32 v94, s1, v10, v22
	v_add3_u32 v95, s0, v10, v22
	v_add3_u32 v96, s18, v10, v22
	v_lshlrev_b32_e32 v10, 8, v11
	v_add3_u32 v29, s19, v10, v22
	v_add_u32_e32 v10, 1, v89
	s_add_i32 s19, 0, 0x21500
	v_lshl_add_u32 v32, v10, 7, s19
	v_xor_b32_e32 v10, v10, v39
	v_lshlrev_b32_e32 v10, 4, v10
	v_and_b32_e32 v33, 0x70, v10
	v_lshlrev_b32_e32 v10, 7, v89
	v_add_u32_e32 v34, s19, v10
	s_add_i32 s19, 0, 0x12800
	s_cmp_lg_u32 s12, 16
	v_add_u32_e32 v36, s19, v10
	v_or_b32_e32 v10, s13, v38
	s_cselect_b64 vcc, -1, 0
	v_xor_b32_e32 v22, v89, v39
	v_cndmask_b32_e32 v98, 64, v10, vcc
	v_bitop3_b32 v10, v38, v39, s13 bitop3:0x36
	v_lshlrev_b32_e32 v22, 4, v22
	v_and_or_b32 v10, v10, 7, v41
	v_and_b32_e32 v35, 0x70, v22
	v_lshlrev_b32_e32 v22, 4, v10
	v_mov_b32_e32 v10, 0
	v_mov_b32_e32 v23, v10
	s_cmp_lg_u32 s20, 16
	v_lshl_add_u64 v[48:49], s[4:5], 0, v[22:23]
	v_or_b32_e32 v22, s3, v38
	s_cselect_b64 vcc, -1, 0
	v_cndmask_b32_e32 v99, 64, v22, vcc
	v_bitop3_b32 v22, v38, v39, s3 bitop3:0x36
	v_and_or_b32 v22, v22, 7, v41
	v_lshlrev_b32_e32 v22, 4, v22
	s_cmp_lg_u32 s14, 16
	v_lshl_add_u64 v[50:51], s[4:5], 0, v[22:23]
	v_or_b32_e32 v22, s15, v38
	s_cselect_b64 vcc, -1, 0
	v_cndmask_b32_e32 v100, 64, v22, vcc
	v_bitop3_b32 v22, v38, v39, s15 bitop3:0x36
	v_and_or_b32 v22, v22, 7, v41
	v_lshlrev_b32_e32 v22, 4, v22
	s_cmp_lg_u32 s16, 16
	v_lshl_add_u64 v[52:53], s[4:5], 0, v[22:23]
	v_or_b32_e32 v22, s17, v38
	s_cselect_b64 vcc, -1, 0
	v_cndmask_b32_e32 v101, 64, v22, vcc
	v_bitop3_b32 v22, v38, v39, s17 bitop3:0x36
	v_and_or_b32 v22, v22, 7, v41
	v_lshlrev_b32_e32 v22, 4, v22
	v_lshl_add_u64 v[54:55], s[4:5], 0, v[22:23]
	v_xor_b32_e32 v22, v38, v20
	s_movk_i32 s10, 0x3700
	v_or_b32_e32 v22, v22, v41
	v_lshlrev_b32_e32 v41, 5, v9
	v_lshrrev_b32_e32 v45, 7, v42
	v_cmp_gt_u32_e64 s[0:1], 16, v40
	v_or_b32_e32 v103, v27, v41
	v_lshl_add_u32 v104, v40, 2, s71
	v_add_u32_e32 v40, s71, v41
	v_lshrrev_b32_e32 v41, 2, v9
	v_mul_lo_u32 v45, v45, s10
	v_or_b32_e32 v41, v90, v41
	v_add_u32_e32 v67, 0, v45
	v_bfe_u32 v45, v42, 3, 4
	v_mul_u32_u24_e32 v41, 0x48, v41
	v_and_b32_e32 v21, 12, v21
	v_mul_u32_u24_e32 v45, 0x48, v45
	v_or_b32_e32 v24, s11, v90
	v_add_lshl_u32 v105, v21, v41, 1
	v_lshl_or_b32 v21, v89, 6, v8
	v_add_lshl_u32 v8, v45, v8, 1
	v_mov_b32_e32 v45, v10
	v_and_b32_e32 v26, 7, v25
	v_lshl_add_u64 v[60:61], s[6:7], 0, v[44:45]
	v_cmp_eq_u32_e64 s[6:7], 0, v42
	v_lshrrev_b32_e32 v42, 3, v24
	v_and_b32_e32 v62, 8, v42
	v_bitop3_b32 v63, v42, v26, 5 bitop3:0x6c
	v_or_b32_e32 v63, v63, v62
	v_lshlrev_b32_e32 v68, 4, v63
	v_add_u32_e32 v63, 64, v24
	v_bitop3_b32 v45, v42, v25, 7 bitop3:0x78
	v_lshrrev_b32_e32 v64, 3, v63
	v_xor_b32_e32 v69, v42, v20
	v_bitop3_b32 v42, v42, v20, 5 bitop3:0x6c
	v_and_b32_e32 v65, 8, v64
	v_or_b32_e32 v42, v42, v62
	v_bitop3_b32 v62, v64, v20, 5 bitop3:0x6c
	v_or_b32_e32 v62, v62, v65
	v_lshlrev_b32_e32 v108, 4, v69
	v_lshlrev_b32_e32 v69, 4, v62
	v_or_b32_e32 v62, 16, v24
	v_lshlrev_b32_e32 v22, 4, v22
	v_lshlrev_b32_e32 v71, 1, v63
	v_lshrrev_b32_e32 v63, 3, v62
	v_lshl_add_u64 v[56:57], s[4:5], 0, v[22:23]
	v_xor_b32_e32 v22, v88, v20
	v_bitop3_b32 v26, v64, v26, 5 bitop3:0x6c
	v_bitop3_b32 v64, v63, v25, 7 bitop3:0x78
	v_lshlrev_b32_e32 v22, 4, v22
	v_or_b32_e32 v26, v26, v65
	v_lshlrev_b32_e32 v111, 4, v64
	v_and_b32_e32 v64, 8, v63
	v_bitop3_b32 v65, v63, v25, 7 bitop3:0x28
	s_movk_i32 s18, 0x48
	v_lshl_add_u64 v[58:59], s[8:9], 0, v[22:23]
	v_or_b32_e32 v23, s11, v9
	v_or_b32_e32 v65, v65, v64
	v_mul_u32_u24_e32 v30, 0x48, v11
	v_mul_u32_u24_e32 v31, 0x48, v9
	v_lshlrev_b32_e32 v97, 2, v11
	v_or_b32_e32 v22, 16, v90
	v_lshlrev_b32_e32 v72, 4, v65
	v_add_u32_e32 v65, 0x50, v24
	v_mul_lo_u32 v23, v23, s18
	v_mad_u32_u24 v11, v11, s18, 32
	v_lshlrev_b32_e32 v70, 1, v24
	v_add_lshl_u32 v109, v24, v30, 1
	v_add_lshl_u32 v110, v24, v31, 1
	v_lshrrev_b32_e32 v73, 3, v65
	v_xor_b32_e32 v75, v63, v20
	v_bitop3_b32 v63, v63, v20, 7 bitop3:0x6c
	v_add_lshl_u32 v113, v62, v30, 1
	v_add_lshl_u32 v115, v30, v90, 1
	v_add_lshl_u32 v116, v22, v30, 1
	v_add_u32_e32 v30, 0x480, v23
	v_add_lshl_u32 v119, v11, v90, 1
	v_add_lshl_u32 v120, v11, v22, 1
	v_or_b32_e32 v11, 32, v90
	v_lshlrev_b32_e32 v123, 2, v24
	v_or_b32_e32 v24, 1, v90
	v_cmp_eq_u32_e32 vcc, v90, v9
	v_lshlrev_b32_e32 v106, 5, v20
	v_and_b32_e32 v74, 8, v73
	v_bitop3_b32 v25, v73, v25, 7 bitop3:0x28
	v_or_b32_e32 v63, v63, v64
	v_bitop3_b32 v20, v73, v20, 7 bitop3:0x6c
	v_lshlrev_b32_e32 v73, 1, v62
	v_add_lshl_u32 v114, v62, v31, 1
	v_add_lshl_u32 v118, v30, v90, 1
	v_add_lshl_u32 v122, v11, v30, 1
	v_lshlrev_b32_e32 v124, 2, v62
	v_or_b32_e32 v30, 2, v90
	v_cndmask_b32_e64 v62, 0, 1.0, vcc
	v_cmp_eq_u32_e32 vcc, v24, v9
	v_lshlrev_b32_e32 v112, 4, v75
	v_lshlrev_b32_e32 v75, 4, v63
	v_add_lshl_u32 v117, v90, v23, 1
	v_add_lshl_u32 v121, v11, v23, 1
	v_add_lshl_u32 v125, v90, v31, 1
	v_add_lshl_u32 v23, v11, v31, 1
	v_or_b32_e32 v31, 3, v90
	v_cndmask_b32_e64 v63, 0, 1.0, vcc
	v_cmp_eq_u32_e32 vcc, v30, v9
	v_cmp_eq_u32_e64 s[4:5], 0, v9
	v_mad_u32_u24 v37, v9, s18, 16
	v_cmp_lt_u32_e64 s[8:9], v90, v9
	v_cmp_gt_u32_e64 s[10:11], v90, v9
	v_cmp_lt_u32_e64 s[12:13], v24, v9
	v_cmp_lt_u32_e64 s[14:15], v30, v9
	v_cmp_gt_u32_e64 s[16:17], v30, v9
	v_cmp_lt_u32_e64 s[18:19], v31, v9
	v_cmp_gt_u32_e64 s[20:21], v31, v9
	v_cndmask_b32_e64 v64, 0, 1.0, vcc
	v_cmp_eq_u32_e32 vcc, v31, v9
	v_lshlrev_b32_e32 v9, 2, v9
	v_lshl_add_u32 v24, v38, 10, s97
	s_mov_b32 s3, 0xdc00
	v_add3_u32 v126, v24, v9, s3
	v_and_b32_e32 v9, 3, v39
	s_movk_i32 s25, 0x2400
	v_lshlrev_b32_e32 v43, 2, v21
	v_lshlrev_b32_e32 v21, 1, v21
	v_lshl_or_b32 v9, v9, 3, s29
	v_lshlrev_b32_e32 v24, 1, v41
	s_waitcnt lgkmcnt(0)
	s_barrier
	v_lshlrev_b32_e32 v66, 2, v89
	v_or_b32_e32 v25, v25, v74
	v_or_b32_e32 v20, v20, v74
	v_add3_u32 v128, v9, v24, s25
	v_mov_b32_e32 v9, 0x3540
	v_add_u32_e32 v151, v67, v8
	v_add_u32_e32 v8, 0, v21
	s_mov_b32 s39, 0
	v_and_b32_e32 v102, 48, v39
	v_lshlrev_b32_e32 v26, 4, v26
	v_lshlrev_b32_e32 v42, 4, v42
	v_lshlrev_b32_e32 v25, 4, v25
	v_lshlrev_b32_e32 v20, 4, v20
	v_lshlrev_b32_e32 v74, 1, v65
	v_add_lshl_u32 v22, v37, v90, 1
	v_add_lshl_u32 v11, v11, v37, 1
	v_writelane_b32 v255, s97, 32
	v_lshl_or_b32 v129, v38, 4, v9
	s_add_i32 s3, 0, 0x15c00
	s_add_i32 s88, s22, 0
	s_add_i32 s89, s23, 0
	s_add_i32 s90, s24, 0
	v_add_u32_e32 v9, 0, v66
	v_add_u32_e32 v152, 0x12800, v8
	v_mbcnt_lo_u32_b32 v8, -1, 0
	s_mov_b64 s[52:53], s[38:39]
	v_add_u32_e32 v107, s70, v89
	v_lshlrev_b32_e32 v45, 4, v45
	v_cndmask_b32_e64 v65, 0, 1.0, vcc
	v_add_u32_e32 v127, 0x2d00, v103
	v_writelane_b32 v255, s29, 44
	v_or_b32_e32 v130, 0x3500, v102
	v_add_u32_e32 v131, v28, v68
	v_add_u32_e32 v132, v28, v26
	v_add_u32_e32 v133, v29, v42
	v_add_u32_e32 v134, v29, v69
	v_add_u32_e32 v135, s3, v70
	v_add_u32_e32 v136, s3, v71
	s_mov_b32 s86, 0x4038aa3b
	s_add_i32 s67, 0, 0x10000
	v_add_u32_e32 v137, v28, v72
	v_add_u32_e32 v138, v28, v25
	v_add_u32_e32 v139, v29, v75
	v_add_u32_e32 v140, v29, v20
	v_add_u32_e32 v141, s3, v73
	v_add_u32_e32 v142, s3, v74
	v_add_u32_e32 v143, v32, v33
	v_add_u32_e32 v145, v34, v35
	s_mov_b32 s87, 0xbfb8aa3b
	v_add_u32_e32 v146, v36, v44
	s_add_i32 s88, s88, 0x23900
	s_add_i32 s89, s89, 0x23900
	s_add_i32 s90, s90, 0x23900
	s_add_i32 s91, 0, 0x27900
	s_add_i32 s92, s81, 0x400
	s_add_i32 s93, s81, 0x800
	s_add_i32 s94, s81, 0xc00
	s_add_i32 s95, s81, 0x1400
	s_add_i32 s96, s81, 0x1800
	s_add_i32 s97, s81, 0x1c00
	s_add_i32 s3, 0, 0x16100
	s_add_i32 s69, 0, 0x18500
	v_mov_b32_e32 v147, 0xbf92477c
	v_add_u32_e32 v148, v40, v27
	s_xor_b64 s[54:55], s[26:27], -1
	v_add_u32_e32 v149, 0, v43
	v_add_u32_e32 v150, 0x12400, v9
	v_mov_b32_e32 v153, 0x3a27c5ac
	v_mbcnt_hi_u32_b32 v144, -1, v8
	v_add_u32_e32 v154, s71, v22
	v_add_u32_e32 v155, s71, v23
	v_add_u32_e32 v156, s71, v11
	s_mov_b32 s33, s28
	s_mov_b32 s29, 0
	v_add_u32_e32 v213, s67, v109
	v_add_u32_e32 v223, s67, v113
	v_add_u32_e32 v208, v94, v108
	v_add_u32_e32 v224, s71, v114
	v_add_u32_e32 v230, s69, v117
	v_add_u32_e32 v238, s69, v122
	v_add_u32_e32 v229, s3, v117
	v_add_u32_e32 v215, v92, v111
	v_add_u32_e32 v236, s69, v121
	v_and_b32_e32 v241, 64, v144
	v_xor_b32_e32 v242, 16, v144
	v_add_u32_e32 v21, 64, v241
	v_cmp_lt_i32_e32 vcc, v242, v21
	s_nop 1
	v_cndmask_b32_e32 v20, v144, v242, vcc
	v_lshlrev_b32_e32 v221, 2, v20
	v_xor_b32_e32 v243, 32, v144
	v_cmp_lt_i32_e32 vcc, v243, v21
	s_nop 1
	v_cndmask_b32_e32 v22, v144, v243, vcc
	v_lshlrev_b32_e32 v222, 2, v22
	v_add_u32_e32 v235, s3, v121
	v_add_u32_e32 v211, v93, v45
	v_add_u32_e32 v233, s67, v119
	v_add_u32_e32 v231, s3, v118
	v_add_u32_e32 v219, v93, v111
	v_add_u32_e32 v217, v95, v112
	v_add_u32_e32 v218, v96, v112
	v_add_u32_e32 v220, v91, v111
	v_add_u32_e32 v237, s3, v122
	v_add_u32_e32 v225, 0x15d80, v44
	v_add_u32_e32 v212, v91, v45
	v_add_u32_e32 v216, v94, v112
	v_add_u32_e32 v227, s67, v115
	v_add_u32_e32 v226, s83, v102
	v_add_u32_e32 v239, 0x12600, v97
	v_add_u32_e32 v232, s69, v118
	v_add_u32_e32 v209, v95, v108
	v_or_b32_e32 v240, v102, v241
	v_add_u32_e32 v234, s67, v120
	v_add_u32_e32 v207, v92, v45
	v_add_u32_e32 v214, s71, v110
	v_add_u32_e32 v228, s67, v116
	v_add_u32_e32 v210, v96, v108
	s_waitcnt vmcnt(0)

.Lp4_oneshot:
	v_mbcnt_lo_u32_b32 v0, -1, 0
	v_mbcnt_hi_u32_b32 v0, -1, v0
	v_lshlrev_b32_e32 v0, 2, v0
	v_lshl_add_u32 v0, s97, 3, v0
	v_add_u32_e32 v0, 0x24000, v0
	v_writelane_b32 v1, s0, 0
	v_writelane_b32 v1, s1, 1
	v_writelane_b32 v1, s2, 2
	v_writelane_b32 v1, s3, 3
	v_writelane_b32 v1, s4, 4
	v_writelane_b32 v1, s5, 5
	v_writelane_b32 v1, s6, 6
	v_writelane_b32 v1, s7, 7
	v_writelane_b32 v1, s8, 8
	v_writelane_b32 v1, s9, 9
	v_writelane_b32 v1, s10, 10
	v_writelane_b32 v1, s11, 11
	v_writelane_b32 v1, s12, 12
	v_writelane_b32 v1, s13, 13
	v_writelane_b32 v1, s14, 14
	v_writelane_b32 v1, s15, 15
	v_writelane_b32 v1, s16, 16
	v_writelane_b32 v1, s17, 17
	v_writelane_b32 v1, s18, 18
	v_writelane_b32 v1, s19, 19
	v_writelane_b32 v1, s20, 20
	v_writelane_b32 v1, s21, 21
	v_writelane_b32 v1, s22, 22
	v_writelane_b32 v1, s23, 23
	v_writelane_b32 v1, s24, 24
	v_writelane_b32 v1, s25, 25
	v_writelane_b32 v1, s26, 26
	v_writelane_b32 v1, s27, 27
	v_writelane_b32 v1, s28, 28
	v_writelane_b32 v1, s29, 29
	v_writelane_b32 v1, s30, 30
	v_writelane_b32 v1, s31, 31
	v_writelane_b32 v1, s32, 32
	v_writelane_b32 v1, s33, 33
	v_writelane_b32 v1, s34, 34
	v_writelane_b32 v1, s35, 35
	v_writelane_b32 v1, s36, 36
	v_writelane_b32 v1, s37, 37
	v_writelane_b32 v1, s38, 38
	v_writelane_b32 v1, s39, 39
	v_writelane_b32 v1, s40, 40
	v_writelane_b32 v1, s41, 41
	v_writelane_b32 v1, s42, 42
	v_writelane_b32 v1, s43, 43
	v_writelane_b32 v1, s44, 44
	v_writelane_b32 v1, s45, 45
	v_writelane_b32 v1, s46, 46
	v_writelane_b32 v1, s47, 47
	v_writelane_b32 v1, s48, 48
	v_writelane_b32 v1, s49, 49
	v_writelane_b32 v1, s50, 50
	v_writelane_b32 v1, s51, 51
	v_writelane_b32 v1, s52, 52
	v_writelane_b32 v1, s53, 53
	v_writelane_b32 v1, s54, 54
	v_writelane_b32 v1, s55, 55
	v_writelane_b32 v1, s56, 56
	v_writelane_b32 v1, s57, 57
	v_writelane_b32 v1, s58, 58
	v_writelane_b32 v1, s59, 59
	v_writelane_b32 v1, s60, 60
	v_writelane_b32 v1, s61, 61
	v_writelane_b32 v1, s62, 62
	v_writelane_b32 v1, s63, 63
	ds_write_b32 v0, v1
	s_nop 1
	v_writelane_b32 v1, s64, 0
	v_writelane_b32 v1, s65, 1
	v_writelane_b32 v1, s66, 2
	v_writelane_b32 v1, s67, 3
	v_writelane_b32 v1, s68, 4
	v_writelane_b32 v1, s69, 5
	v_writelane_b32 v1, s70, 6
	v_writelane_b32 v1, s71, 7
	v_writelane_b32 v1, s72, 8
	v_writelane_b32 v1, s73, 9
	v_writelane_b32 v1, s74, 10
	v_writelane_b32 v1, s75, 11
	v_writelane_b32 v1, s76, 12
	v_writelane_b32 v1, s77, 13
	v_writelane_b32 v1, s78, 14
	v_writelane_b32 v1, s79, 15
	v_writelane_b32 v1, s80, 16
	v_writelane_b32 v1, s81, 17
	v_writelane_b32 v1, s82, 18
	v_writelane_b32 v1, s83, 19
	v_writelane_b32 v1, s84, 20
	v_writelane_b32 v1, s85, 21
	v_writelane_b32 v1, s86, 22
	v_writelane_b32 v1, s87, 23
	v_writelane_b32 v1, s88, 24
	v_writelane_b32 v1, s89, 25
	v_writelane_b32 v1, s90, 26
	v_writelane_b32 v1, s91, 27
	v_writelane_b32 v1, s92, 28
	v_writelane_b32 v1, s93, 29
	v_writelane_b32 v1, s94, 30
	v_writelane_b32 v1, s95, 31
	v_writelane_b32 v1, s96, 32
	v_writelane_b32 v1, s97, 33
	ds_write_b32 v0, v1 offset:256
	s_waitcnt lgkmcnt(0)
	s_add_u32 s3, s76, 0x7a00000
	s_addc_u32 s33, s77, 0
	s_add_u32 s50, s76, 0x1a00000
	s_addc_u32 s51, s77, 0
	s_add_u32 s4, s76, 0x2200000
	s_addc_u32 s5, s77, 0
	s_add_u32 s6, s76, 0x2800000
	s_addc_u32 s7, s77, 0
	s_add_u32 s8, s76, 0xbb00000
	s_addc_u32 s9, s77, 0
	s_add_u32 s10, s76, 0x1f00000
	s_addc_u32 s11, s77, 0
	s_add_u32 s12, s76, 0x18000
	v_readlane_b32 s0, v255, 31
	s_addc_u32 s13, s77, 0
	s_bfe_u32 s52, s96, 0x20006
	s_lshl_b32 s53, s0, 10
	s_lshr_b32 s0, s96, 8
	s_lshl_b32 s54, s0, 6
	s_lshl_b32 s55, s0, 13
	s_lshl_b32 s56, s52, 12
	s_cmp_eq_u32 s0, 1
	s_cselect_b64 s[14:15], -1, 0
	s_lshl_b32 s57, s52, 6
	s_cmpk_lt_u32 s96, 0x100
	s_cselect_b64 s[16:17], -1, 0
	s_add_u32 s58, s76, 0x20000
	s_addc_u32 s59, s77, 0
	s_add_u32 s60, s76, 0x7a40080
	s_addc_u32 s61, s77, 0
	s_add_u32 s62, s76, 0x1a00100
	s_addc_u32 s63, s77, 0
	s_add_i32 s64, 0, 0x27e40
	v_mbcnt_lo_u32_b32 v0, -1, 0
	v_mov_b32_e32 v129, 0
	s_mov_b32 s19, 0
	v_mov_b32_e32 v140, 1
	s_mov_b32 s65, 0x1fffe0
	s_mov_b64 s[20:21], 0x80
	s_movk_i32 s66, 0x3c0
	s_mov_b64 s[22:23], 0x100
	s_mov_b32 s67, 0x8080
	v_mov_b32_e32 v141, s64
	v_mbcnt_hi_u32_b32 v142, -1, v0
	v_mov_b32_e32 v143, 0
	s_branch .Lp4_enter
.Lp4_return:
	v_mbcnt_lo_u32_b32 v0, -1, 0
	v_mbcnt_hi_u32_b32 v0, -1, v0
	v_lshlrev_b32_e32 v0, 2, v0
	v_lshl_add_u32 v0, s97, 3, v0
	v_add_u32_e32 v0, 0x24000, v0
	ds_read_b32 v1, v0
	ds_read_b32 v2, v0 offset:256
	s_waitcnt lgkmcnt(0)
	v_readlane_b32 s0, v1, 0
	v_readlane_b32 s1, v1, 1
	v_readlane_b32 s2, v1, 2
	v_readlane_b32 s3, v1, 3
	v_readlane_b32 s4, v1, 4
	v_readlane_b32 s5, v1, 5
	v_readlane_b32 s6, v1, 6
	v_readlane_b32 s7, v1, 7
	v_readlane_b32 s8, v1, 8
	v_readlane_b32 s9, v1, 9
	v_readlane_b32 s10, v1, 10
	v_readlane_b32 s11, v1, 11
	v_readlane_b32 s12, v1, 12
	v_readlane_b32 s13, v1, 13
	v_readlane_b32 s14, v1, 14
	v_readlane_b32 s15, v1, 15
	v_readlane_b32 s16, v1, 16
	v_readlane_b32 s17, v1, 17
	v_readlane_b32 s18, v1, 18
	v_readlane_b32 s19, v1, 19
	v_readlane_b32 s20, v1, 20
	v_readlane_b32 s21, v1, 21
	v_readlane_b32 s22, v1, 22
	v_readlane_b32 s23, v1, 23
	v_readlane_b32 s24, v1, 24
	v_readlane_b32 s25, v1, 25
	v_readlane_b32 s26, v1, 26
	v_readlane_b32 s27, v1, 27
	v_readlane_b32 s28, v1, 28
	v_readlane_b32 s29, v1, 29
	v_readlane_b32 s30, v1, 30
	v_readlane_b32 s31, v1, 31
	v_readlane_b32 s32, v1, 32
	v_readlane_b32 s33, v1, 33
	v_readlane_b32 s34, v1, 34
	v_readlane_b32 s35, v1, 35
	v_readlane_b32 s36, v1, 36
	v_readlane_b32 s37, v1, 37
	v_readlane_b32 s38, v1, 38
	v_readlane_b32 s39, v1, 39
	v_readlane_b32 s40, v1, 40
	v_readlane_b32 s41, v1, 41
	v_readlane_b32 s42, v1, 42
	v_readlane_b32 s43, v1, 43
	v_readlane_b32 s44, v1, 44
	v_readlane_b32 s45, v1, 45
	v_readlane_b32 s46, v1, 46
	v_readlane_b32 s47, v1, 47
	v_readlane_b32 s48, v1, 48
	v_readlane_b32 s49, v1, 49
	v_readlane_b32 s50, v1, 50
	v_readlane_b32 s51, v1, 51
	v_readlane_b32 s52, v1, 52
	v_readlane_b32 s53, v1, 53
	v_readlane_b32 s54, v1, 54
	v_readlane_b32 s55, v1, 55
	v_readlane_b32 s56, v1, 56
	v_readlane_b32 s57, v1, 57
	v_readlane_b32 s58, v1, 58
	v_readlane_b32 s59, v1, 59
	v_readlane_b32 s60, v1, 60
	v_readlane_b32 s61, v1, 61
	v_readlane_b32 s62, v1, 62
	v_readlane_b32 s63, v1, 63
	v_readlane_b32 s64, v2, 0
	v_readlane_b32 s65, v2, 1
	v_readlane_b32 s66, v2, 2
	v_readlane_b32 s67, v2, 3
	v_readlane_b32 s68, v2, 4
	v_readlane_b32 s69, v2, 5
	v_readlane_b32 s70, v2, 6
	v_readlane_b32 s71, v2, 7
	v_readlane_b32 s72, v2, 8
	v_readlane_b32 s73, v2, 9
	v_readlane_b32 s74, v2, 10
	v_readlane_b32 s75, v2, 11
	v_readlane_b32 s76, v2, 12
	v_readlane_b32 s77, v2, 13
	v_readlane_b32 s78, v2, 14
	v_readlane_b32 s79, v2, 15
	v_readlane_b32 s80, v2, 16
	v_readlane_b32 s81, v2, 17
	v_readlane_b32 s82, v2, 18
	v_readlane_b32 s83, v2, 19
	v_readlane_b32 s84, v2, 20
	v_readlane_b32 s85, v2, 21
	v_readlane_b32 s86, v2, 22
	v_readlane_b32 s87, v2, 23
	v_readlane_b32 s88, v2, 24
	v_readlane_b32 s89, v2, 25
	v_readlane_b32 s90, v2, 26
	v_readlane_b32 s91, v2, 27
	v_readlane_b32 s92, v2, 28
	v_readlane_b32 s93, v2, 29
	v_readlane_b32 s94, v2, 30
	v_readlane_b32 s95, v2, 31
	v_readlane_b32 s96, v2, 32
	v_readlane_b32 s97, v2, 33
	s_nop 7
	s_barrier
	s_branch .Lmq_setup

.Lpk_top:
	v_mov_b32_e32 v0, s48
	ds_write_b32 v0, v129 offset:8
	global_load_dword v1, v129, s[76:77] offset:2560 sc1
	s_waitcnt vmcnt(0)
	v_readfirstlane_b32 s4, v1
	s_nop 1
	s_cmpk_gt_u32 s4, 0x1ff
	s_cbranch_scc1 .Lpk_claim
	s_lshr_b32 s12, s4, 2
	s_and_b32 s12, s12, 7
	s_lshl_b32 s12, s12, 4
	s_lshr_b32 s13, s4, 5
	s_add_i32 s12, s12, s13
	s_lshl_b32 s12, s12, 8
	v_mov_b32_e32 v0, s12
	global_load_dword v1, v0, s[72:73] sc1
	s_waitcnt vmcnt(0)
	v_readfirstlane_b32 s12, v1
	s_nop 1
	s_cmp_gt_u32 s12, 15
	s_cbranch_scc1 .Lpk_claim
	s_and_b32 s12, s2, 7
	s_lshl_b32 s13, s12, 7
	v_mov_b32_e32 v0, s13
	global_load_dword v1, v0, s[76:77] offset:3072 sc1
	s_waitcnt vmcnt(0)
	v_readfirstlane_b32 s13, v1
	s_nop 1
	s_cmp_gt_u32 s13, 63
	s_cbranch_scc1 .Lpk_sleep
	s_lshr_b32 s13, s13, 2
	s_lshl_b32 s14, s12, 4
	s_add_i32 s13, s13, s14
	s_lshl_b32 s13, s13, 8
	v_mov_b32_e32 v2, s13
	global_load_dword v1, v2, s[56:57] sc1
	s_waitcnt vmcnt(0)
	v_readfirstlane_b32 s13, v1
	s_nop 1
	s_cmp_gt_u32 s13, 3
	s_cbranch_scc0 .Lpk_sleep
	v_mov_b32_e32 v1, 1
	global_atomic_add v1, v0, v1, s[76:77] offset:3072 sc0
	s_waitcnt vmcnt(0)
	v_readfirstlane_b32 s13, v1
	s_nop 1
	s_cmp_gt_u32 s13, 63
	s_cbranch_scc1 .Lpk_sleep
	s_lshr_b32 s14, s13, 2
	s_lshl_b32 s15, s12, 4
	s_add_i32 s14, s14, s15
	s_lshl_b32 s14, s14, 8
	v_mov_b32_e32 v2, s14
.Lpk_wait:
	global_load_dword v1, v2, s[56:57] sc1
	s_waitcnt vmcnt(0)
	v_readfirstlane_b32 s14, v1
	s_nop 1
	s_cmp_gt_u32 s14, 3
	s_cbranch_scc1 .Lpk_go
	s_sleep 8
	s_branch .Lpk_wait
.Lpk_go:
	buffer_inv sc1
	s_waitcnt vmcnt(0)
	s_lshl_b32 s12, s12, 6
	s_add_i32 s12, s12, s13
	v_mov_b32_e32 v2, s12
	v_mov_b32_e32 v0, s48
	ds_write_b32 v0, v2
	v_mov_b32_e32 v2, 1
	ds_write_b32 v0, v2 offset:8
	s_branch .LBB0_1228
.Lpk_sleep:
	s_sleep 8
	s_branch .Lpk_top
.Lpk_claim:
	s_mov_b64 s[14:15], exec
	v_mbcnt_lo_u32_b32 v0, s14, 0
	v_mbcnt_hi_u32_b32 v0, s15, v0
	v_cmp_eq_u32_e32 vcc, 0, v0
	s_and_saveexec_b64 s[12:13], vcc
	s_cbranch_execz .LBB0_1204
	s_bcnt1_i32_b64 s4, s[14:15]
	v_mov_b32_e32 v1, s4
	global_atomic_add v1, v129, v1, s[76:77] offset:2560 sc0

.LBB0_1228:
	s_or_b64 exec, exec, s[10:11]
	s_waitcnt lgkmcnt(0)
	s_barrier
	ds_read_b32 v0, v140
	s_mov_b64 s[10:11], -1
	s_waitcnt lgkmcnt(0)
	v_readfirstlane_b32 s14, v0
	ds_read_b32 v1, v140 offset:8
	s_waitcnt lgkmcnt(0)
	v_readfirstlane_b32 s12, v1
	s_nop 1
	s_cmp_eq_u32 s12, 1
	s_cbranch_scc1 .Lp4_oneshot
	s_cmpk_gt_u32 s14, 0x1ff
	s_cbranch_scc1 .LBB0_1200
	v_mbcnt_lo_u32_b32 v2, -1, 0
	v_mbcnt_hi_u32_b32 v2, -1, v2
	s_lshl_b32 s4, s14, 2
	v_lshl_or_b32 v4, v2, 4, s66
	v_ashrrev_i32_e32 v0, 31, v4
	v_lshrrev_b32_e32 v0, 22, v0
	v_add_u32_e32 v0, v4, v0
	v_ashrrev_i32_e32 v0, 10, v0
	v_mul_i32_i24_e32 v1, 0x400, v0
	v_sub_u32_e32 v1, v4, v1
	v_lshrrev_b32_e32 v3, 4, v1
	v_bitop3_b32 v3, v3, v1, 32 bitop3:0x6c
	v_lshlrev_b32_e32 v1, 3, v0
	v_and_b32_e32 v5, -16, v1
	v_ashrrev_i32_e32 v1, 31, v3
	v_lshrrev_b32_e32 v1, 26, v1
	v_add_u32_e32 v6, v3, v1
	v_ashrrev_i32_e32 v1, 6, v6
	v_and_b32_e32 v6, 0xc0, v6
	v_sub_u32_e32 v3, v3, v6
	v_lshlrev_b32_e32 v7, 5, v0
	v_ashrrev_i16_sdwa v3, v141, sext(v3) dst_sel:DWORD dst_unused:UNUSED_PAD src0_sel:DWORD src1_sel:BYTE_0
	v_and_b32_e32 v7, 32, v7
	v_bfe_i32 v3, v3, 0, 16
	v_add_u32_e32 v5, v1, v5
	v_and_b32_e32 v9, 3, v1
	v_add_lshl_u32 v7, v7, v3, 1
	v_lshlrev_b32_e32 v6, 1, v5
	v_lshrrev_b32_e32 v8, 2, v5
	v_and_or_b32 v9, v5, s49, v9
	v_lshl_add_u32 v130, v5, 11, v7
	v_add_u32_e32 v5, 0x2000, v4
	v_ashrrev_i32_e32 v4, 31, v5
	v_lshrrev_b32_e32 v4, 22, v4
	v_and_b32_e32 v6, 24, v6
	v_and_b32_e32 v8, 4, v8
	v_add_u32_e32 v4, v5, v4
	v_or3_b32 v6, v9, v8, v6
	v_ashrrev_i32_e32 v4, 10, v4
	v_lshl_add_u32 v128, v6, 11, v7
	v_mul_i32_i24_e32 v6, 0x400, v4
	v_sub_u32_e32 v5, v5, v6
	v_lshrrev_b32_e32 v6, 4, v5
	v_bitop3_b32 v6, v6, v5, 32 bitop3:0x6c
	v_lshlrev_b32_e32 v5, 3, v4
	v_and_b32_e32 v7, -16, v5
	v_ashrrev_i32_e32 v5, 31, v6
	v_lshrrev_b32_e32 v5, 26, v5
	s_and_b32 s4, s4, 0x70
	s_lshr_b32 s15, s14, 5
	v_add_u32_e32 v8, v6, v5
	s_or_b32 s4, s4, s15
	v_ashrrev_i32_e32 v5, 6, v8
	v_and_b32_e32 v8, 0xffc0, v8
	s_and_b32 s20, s14, 3
	v_sub_u32_e32 v6, v6, v8
	s_lshl_b32 s21, s4, 19
	v_lshrrev_b16_e32 v8, 7, v6
	s_add_u32 s10, s64, s21
	v_and_b32_e32 v8, 1, v8
	s_addc_u32 s11, s65, 0
	s_lshl_b32 s16, s20, 19
	v_add_u32_e32 v7, v5, v7
	v_add_u16_e32 v6, v6, v8
	s_add_u32 s12, s50, s16
	v_lshlrev_b32_e32 v9, 5, v4
	v_ashrrev_i16_sdwa v6, v141, sext(v6) dst_sel:DWORD dst_unused:UNUSED_PAD src0_sel:DWORD src1_sel:BYTE_0
	v_lshlrev_b32_e32 v8, 1, v7
	v_lshrrev_b32_e32 v10, 2, v7
	v_and_b32_e32 v11, 3, v5
	s_addc_u32 s13, s51, 0
	s_add_i32 s30, s66, 0
	v_and_b32_e32 v9, 32, v9
	v_bfe_i32 v6, v6, 0, 16
	v_and_b32_e32 v8, 24, v8
	v_and_b32_e32 v10, 4, v10
	v_and_or_b32 v11, v7, s49, v11
	s_add_i32 m0, s30, 0x10000
	v_or3_b32 v8, v11, v10, v8
	v_add_lshl_u32 v9, v9, v6, 1
	global_load_lds_dwordx4 v128, s[12:13]
	s_add_i32 m0, s30, 0x12000
	v_lshl_add_u32 v134, v8, 11, v9
	s_add_u32 s18, s12, 0x40000
	global_load_lds_dwordx4 v134, s[12:13]
	s_addc_u32 s19, s13, 0
	s_add_i32 m0, s30, 0x14000
	s_add_i32 s31, s30, 0x2000
	global_load_lds_dwordx4 v128, s[18:19]
	s_add_i32 m0, s30, 0x16000
	v_lshl_add_u32 v132, v7, 11, v9
	global_load_lds_dwordx4 v134, s[18:19]
	s_mov_b32 m0, s30
	s_add_u32 s18, s10, 0x40000
	global_load_lds_dwordx4 v130, s[10:11]
	s_mov_b32 m0, s31
	s_addc_u32 s19, s11, 0
	s_add_i32 s34, s30, 0x4000
	global_load_lds_dwordx4 v132, s[10:11]
	s_mov_b32 m0, s34
	s_add_i32 s35, s30, 0x6000
	v_lshl_add_u64 v[8:9], s[12:13], 0, v[128:129]
	v_mov_b32_e32 v135, v129
	global_load_lds_dwordx4 v130, s[18:19]
	s_mov_b32 m0, s35
	v_lshl_add_u64 v[10:11], s[12:13], 0, v[134:135]
	v_mov_b32_e32 v131, v129
	global_load_lds_dwordx4 v132, s[18:19]
	v_lshl_add_u64 v[8:9], v[8:9], 0, s[6:7]
	s_add_i32 m0, s30, 0x18000
	v_lshl_add_u64 v[12:13], s[10:11], 0, v[130:131]
	v_mov_b32_e32 v133, v129
	global_load_lds_dwordx4 v[8:9], off
	v_lshl_add_u64 v[8:9], v[10:11], 0, s[6:7]
	s_add_i32 m0, s30, 0x1a000
	s_add_i32 s36, s30, 0x8000
	v_lshl_add_u64 v[14:15], s[10:11], 0, v[132:133]
	global_load_lds_dwordx4 v[8:9], off
	v_lshl_add_u64 v[8:9], v[12:13], 0, s[6:7]
	s_mov_b32 m0, s36
	s_add_i32 s37, s30, 0xa000
	global_load_lds_dwordx4 v[8:9], off
	v_lshl_add_u64 v[8:9], v[14:15], 0, s[6:7]
	s_mov_b32 m0, s37
	s_add_u32 s18, s12, 0x40080
	global_load_lds_dwordx4 v[8:9], off
	s_addc_u32 s19, s13, 0
	s_add_i32 m0, s30, 0x1c000
	s_and_b64 vcc, exec, s[0:1]
	global_load_lds_dwordx4 v128, s[18:19]
	s_add_i32 m0, s30, 0x1e000
	s_nop 0
	global_load_lds_dwordx4 v134, s[18:19]
	s_cbranch_vccnz .LBB0_1231
	s_barrier

.LBB0_1294:
	ds_read_b32 v0, v141 offset:8
	s_waitcnt lgkmcnt(0)
	v_readfirstlane_b32 s0, v0
	s_nop 1
	s_cmp_eq_u32 s0, 1
	s_cbranch_scc1 .Lp4_return
	v_mbcnt_lo_u32_b32 v0, -1, 0
	v_mbcnt_hi_u32_b32 v0, -1, v0
	s_nop 0
	v_or_b32_e32 v0, s97, v0
	v_cmp_eq_u32_e32 vcc, 0, v0
	s_and_saveexec_b64 s[0:1], vcc
	s_cbranch_execz .LBB0_1325
	s_mov_b64 s[24:25], 0
	s_branch .LBB0_1297

.Lp4_enter:
	ds_read_b32 v0, v141
	s_waitcnt lgkmcnt(0)
	v_readfirstlane_b32 s0, v0
	s_cmp_eq_u32 s0, -1
	s_cbranch_scc1 .LBB0_1383
	v_mbcnt_lo_u32_b32 v1, -1, 0
	v_mbcnt_hi_u32_b32 v1, -1, v1
	s_lshr_b32 s18, s0, 2
	v_lshl_or_b32 v4, v1, 4, s53
	v_ashrrev_i32_e32 v0, 31, v4
	v_lshrrev_b32_e32 v0, 22, v0
	v_add_u32_e32 v0, v4, v0
	v_ashrrev_i32_e32 v0, 10, v0
	v_mul_i32_i24_e32 v2, 0x400, v0
	v_sub_u32_e32 v2, v4, v2
	v_lshrrev_b32_e32 v3, 4, v2
	v_bitop3_b32 v3, v3, v2, 32 bitop3:0x6c
	v_lshlrev_b32_e32 v2, 3, v0
	v_and_b32_e32 v5, -16, v2
	v_ashrrev_i32_e32 v2, 31, v3
	v_lshrrev_b32_e32 v2, 26, v2
	v_add_u32_e32 v6, v3, v2
	v_ashrrev_i32_e32 v2, 6, v6
	v_and_b32_e32 v6, 0xc0, v6
	v_sub_u32_e32 v3, v3, v6
	v_lshlrev_b32_e32 v7, 5, v0
	v_ashrrev_i16_sdwa v3, v140, sext(v3) dst_sel:DWORD dst_unused:UNUSED_PAD src0_sel:DWORD src1_sel:BYTE_0
	v_and_b32_e32 v7, 32, v7
	v_bfe_i32 v3, v3, 0, 16
	v_add_u32_e32 v5, v2, v5
	v_and_b32_e32 v9, 3, v2
	v_add_lshl_u32 v7, v7, v3, 1
	v_lshlrev_b32_e32 v6, 1, v5
	v_lshrrev_b32_e32 v8, 2, v5
	v_and_or_b32 v9, v5, s65, v9
	v_lshl_add_u32 v130, v5, 11, v7
	v_add_u32_e32 v5, 0x2000, v4
	v_ashrrev_i32_e32 v4, 31, v5
	v_lshrrev_b32_e32 v4, 22, v4
	v_and_b32_e32 v6, 24, v6
	v_and_b32_e32 v8, 4, v8
	v_add_u32_e32 v4, v5, v4
	v_or3_b32 v6, v9, v8, v6
	v_ashrrev_i32_e32 v4, 10, v4
	v_lshl_add_u32 v128, v6, 11, v7
	v_mul_i32_i24_e32 v6, 0x400, v4
	v_sub_u32_e32 v5, v5, v6
	v_lshrrev_b32_e32 v6, 4, v5
	v_bitop3_b32 v6, v6, v5, 32 bitop3:0x6c
	v_lshlrev_b32_e32 v5, 3, v4
	v_and_b32_e32 v7, -16, v5
	v_ashrrev_i32_e32 v5, 31, v6
	v_lshrrev_b32_e32 v5, 26, v5
	v_add_u32_e32 v8, v6, v5
	v_ashrrev_i32_e32 v5, 6, v8
	v_and_b32_e32 v8, 0xffc0, v8
	v_sub_u32_e32 v6, v6, v8
	s_and_b32 s34, s0, 3
	v_lshrrev_b16_e32 v8, 7, v6
	v_and_b32_e32 v8, 1, v8
	s_lshl_b64 s[26:27], s[18:19], 19
	s_lshl_b32 s28, s34, 19
	v_add_u32_e32 v7, v5, v7
	v_add_u16_e32 v6, v6, v8
	s_add_u32 s0, s50, s28
	v_lshlrev_b32_e32 v9, 5, v4
	v_ashrrev_i16_sdwa v6, v140, sext(v6) dst_sel:DWORD dst_unused:UNUSED_PAD src0_sel:DWORD src1_sel:BYTE_0
	v_lshlrev_b32_e32 v8, 1, v7
	v_lshrrev_b32_e32 v10, 2, v7
	v_and_b32_e32 v11, 3, v5
	s_addc_u32 s1, s51, 0
	s_add_i32 s35, s53, 0
	v_and_b32_e32 v9, 32, v9
	v_bfe_i32 v6, v6, 0, 16
	v_and_b32_e32 v8, 24, v8
	v_and_b32_e32 v10, 4, v10
	v_and_or_b32 v11, v7, s65, v11
	s_add_i32 m0, s35, 0x10000
	v_or3_b32 v8, v11, v10, v8
	v_add_lshl_u32 v9, v9, v6, 1
	global_load_lds_dwordx4 v128, s[0:1]
	s_add_i32 m0, s35, 0x12000
	v_lshl_add_u32 v134, v8, 11, v9
	s_add_u32 s24, s0, 0x40000
	global_load_lds_dwordx4 v134, s[0:1]
	s_addc_u32 s25, s1, 0
	s_add_i32 m0, s35, 0x14000
	v_lshl_add_u32 v132, v7, 11, v9
	global_load_lds_dwordx4 v128, s[24:25]
	s_add_i32 m0, s35, 0x16000
	v_lshl_add_u64 v[8:9], s[0:1], 0, v[128:129]
	global_load_lds_dwordx4 v134, s[24:25]
	s_add_u32 s24, s3, s26
	s_addc_u32 s25, s33, s27
	s_add_i32 s36, s35, 0x2000
	s_mov_b32 m0, s35
	s_add_u32 s30, s24, 0x40000
	global_load_lds_dwordx4 v130, s[24:25]
	s_mov_b32 m0, s36
	s_addc_u32 s31, s25, 0
	s_add_i32 s37, s35, 0x4000
	global_load_lds_dwordx4 v132, s[24:25]
	s_mov_b32 m0, s37
	s_add_i32 s38, s35, 0x6000
	v_mov_b32_e32 v135, v129
	global_load_lds_dwordx4 v130, s[30:31]
	s_mov_b32 m0, s38
	v_lshl_add_u64 v[10:11], s[0:1], 0, v[134:135]
	v_mov_b32_e32 v131, v129
	global_load_lds_dwordx4 v132, s[30:31]
	v_lshl_add_u64 v[8:9], v[8:9], 0, s[20:21]
	s_add_i32 m0, s35, 0x18000
	v_lshl_add_u64 v[12:13], s[24:25], 0, v[130:131]
	v_mov_b32_e32 v133, v129
	global_load_lds_dwordx4 v[8:9], off
	v_lshl_add_u64 v[8:9], v[10:11], 0, s[20:21]
	s_add_i32 m0, s35, 0x1a000
	s_add_i32 s39, s35, 0x8000
	v_lshl_add_u64 v[14:15], s[24:25], 0, v[132:133]
	global_load_lds_dwordx4 v[8:9], off
	v_lshl_add_u64 v[8:9], v[12:13], 0, s[20:21]
	s_mov_b32 m0, s39
	s_add_i32 s40, s35, 0xa000
	global_load_lds_dwordx4 v[8:9], off
	v_lshl_add_u64 v[8:9], v[14:15], 0, s[20:21]
	s_mov_b32 m0, s40
	s_add_u32 s30, s0, 0x40080
	global_load_lds_dwordx4 v[8:9], off
	s_addc_u32 s31, s1, 0
	s_add_i32 m0, s35, 0x1c000
	s_andn2_b64 vcc, exec, s[14:15]
	global_load_lds_dwordx4 v128, s[30:31]
	s_add_i32 m0, s35, 0x1e000
	s_nop 0
	global_load_lds_dwordx4 v134, s[30:31]
	s_cbranch_vccnz .LBB0_1328
	s_barrier
